# grid barrier: XCD leader also invalidates early (right after its TOP arrival), no wait before the local release
# baseline (speedup 1.0000x reference)
; __device__ __forceinline__ unsigned xb_ld(unsigned* p)              { return __hip_atomic_load(p, __ATOMIC_RELAXED, __HIP_MEMORY_SCOPE_AGENT); }
; __device__ __forceinline__ unsigned xb_add(unsigned* p, unsigned v) { return __hip_atomic_fetch_add(p, v, __ATOMIC_RELAXED, __HIP_MEMORY_SCOPE_AGENT); }
; #define XB_SPIN(cond, bar) do { unsigned _sp = 0; while (cond) { __builtin_amdgcn_s_sleep(1); \
;     if ((++_sp & 255u) == 0u) { if (xb_ld(&(bar)[XB_TMO])) break; if (_sp > XB_SPIN_CAP) { atomicAdd(&(bar)[XB_TMO], 1u); break; } } } } while (0)
; template <bool FLUSH> __device__ __forceinline__ void xcd_barrier(const XcdBarrier& b) {
;     ...
;         const unsigned old = xb_add(&bar[XB_XSUB(b.x)], 1u);
;         const unsigned gen = old / nloc;
;         if (old + 1u == (gen + 1u) * nloc) {
;             if (FLUSH) __builtin_amdgcn_fence(__ATOMIC_RELEASE, "agent");
;             asm volatile("s_waitcnt vmcnt(0)" ::: "memory");
;             const unsigned og = xb_add(&bar[XB_TOP], 1u);
;             const unsigned tg = og / nx;
;             if (og + 1u == (tg + 1u) * nx) xb_add(&bar[XB_TOPGEN], 1u);
;             else XB_SPIN(xb_ld(&bar[XB_TOPGEN]) == tg, bar);
;             __builtin_amdgcn_fence(__ATOMIC_ACQUIRE, "agent");
;             xb_add(&bar[XB_XGEN(b.x)], 1u);
.LBB0_100:
	s_andn2_saveexec_b64 s[6:7], s[6:7]
	s_cbranch_execz .LBB0_116
	buffer_wbl2 sc1
	s_waitcnt lgkmcnt(0)
	s_waitcnt vmcnt(0)
	v_mov_b32_e32 v1, 0x3000
	v_mov_b32_e32 v2, 1
	global_atomic_add v1, v1, v2, s[42:43] offset:1024 sc0
	v_cvt_f32_u32_e32 v2, v0
	v_sub_u32_e32 v3, 0, v0
	s_add_u32 s6, s42, 0x3500
	s_addc_u32 s7, s43, 0
	v_rcp_iflag_f32_e32 v2, v2
	s_mov_b64 s[10:11], -1
	v_mul_f32_e32 v2, 0x4f7ffffe, v2
	v_cvt_u32_f32_e32 v2, v2
	v_mul_lo_u32 v3, v3, v2
	v_mul_hi_u32 v3, v2, v3
	v_add_u32_e32 v2, v2, v3
	s_waitcnt vmcnt(0)
	buffer_inv sc1
	v_mul_hi_u32 v2, v1, v2
	v_mul_lo_u32 v4, v2, v0
	v_add_u32_e32 v3, 1, v1
	v_sub_u32_e32 v1, v1, v4
	v_add_u32_e32 v5, 1, v2
	v_cmp_ge_u32_e32 vcc, v1, v0
	v_sub_u32_e32 v4, v1, v0
	s_nop 0
	v_cndmask_b32_e32 v2, v2, v5, vcc
	v_cndmask_b32_e32 v1, v1, v4, vcc
	v_add_u32_e32 v4, 1, v2
	v_cmp_ge_u32_e32 vcc, v1, v0
	s_nop 1
	v_cndmask_b32_e32 v2, v2, v4, vcc
	v_mul_lo_u32 v1, v0, v2
	v_add_u32_e32 v0, v1, v0
	v_cmp_ne_u32_e32 vcc, v3, v0
	v_mov_b64_e32 v[0:1], s[6:7]
	s_and_saveexec_b64 s[8:9], vcc
	s_cbranch_execz .LBB0_113
	v_mov_b32_e32 v0, 0
	global_load_dword v1, v0, s[6:7] sc1
	s_mov_b64 s[14:15], 0
	s_waitcnt vmcnt(0)
	v_cmp_eq_u32_e32 vcc, v1, v2
	s_and_saveexec_b64 s[12:13], vcc
	s_cbranch_execz .LBB0_112
	s_add_u32 s10, s42, 0x200
	s_addc_u32 s11, s43, 0
	s_mov_b32 s24, 1
	s_branch .LBB0_105

; __device__ __forceinline__ unsigned xb_ld(unsigned* p)              { return __hip_atomic_load(p, __ATOMIC_RELAXED, __HIP_MEMORY_SCOPE_AGENT); }
; __device__ __forceinline__ unsigned xb_add(unsigned* p, unsigned v) { return __hip_atomic_fetch_add(p, v, __ATOMIC_RELAXED, __HIP_MEMORY_SCOPE_AGENT); }
; #define XB_SPIN(cond, bar) do { unsigned _sp = 0; while (cond) { __builtin_amdgcn_s_sleep(1); \
;     if ((++_sp & 255u) == 0u) { if (xb_ld(&(bar)[XB_TMO])) break; if (_sp > XB_SPIN_CAP) { atomicAdd(&(bar)[XB_TMO], 1u); break; } } } } while (0)
; template <bool FLUSH> __device__ __forceinline__ void xcd_barrier(const XcdBarrier& b) {
;     ...
;             if (og + 1u == (tg + 1u) * nx) xb_add(&bar[XB_TOPGEN], 1u);
;             else XB_SPIN(xb_ld(&bar[XB_TOPGEN]) == tg, bar);
;             __builtin_amdgcn_fence(__ATOMIC_ACQUIRE, "agent");
;             xb_add(&bar[XB_XGEN(b.x)], 1u);
;             asm volatile("s_waitcnt vmcnt(0)" ::: "memory");
.LBB0_115:
	s_or_b64 exec, exec, s[6:7]
	v_mov_b32_e32 v0, 0x2000
	v_mov_b32_e32 v1, 1
	global_atomic_add v0, v1, s[4:5] offset:1024
	s_waitcnt vmcnt(0)

; __device__ __forceinline__ unsigned xb_ld(unsigned* p)              { return __hip_atomic_load(p, __ATOMIC_RELAXED, __HIP_MEMORY_SCOPE_AGENT); }
; __device__ __forceinline__ unsigned xb_add(unsigned* p, unsigned v) { return __hip_atomic_fetch_add(p, v, __ATOMIC_RELAXED, __HIP_MEMORY_SCOPE_AGENT); }
; #define XB_SPIN(cond, bar) do { unsigned _sp = 0; while (cond) { __builtin_amdgcn_s_sleep(1); \
;     if ((++_sp & 255u) == 0u) { if (xb_ld(&(bar)[XB_TMO])) break; if (_sp > XB_SPIN_CAP) { atomicAdd(&(bar)[XB_TMO], 1u); break; } } } } while (0)
; template <bool FLUSH> __device__ __forceinline__ void xcd_barrier(const XcdBarrier& b) {
;     ...
;         const unsigned old = xb_add(&bar[XB_XSUB(b.x)], 1u);
;         const unsigned gen = old / nloc;
;         if (old + 1u == (gen + 1u) * nloc) {
;             if (FLUSH) __builtin_amdgcn_fence(__ATOMIC_RELEASE, "agent");
;             asm volatile("s_waitcnt vmcnt(0)" ::: "memory");
;             const unsigned og = xb_add(&bar[XB_TOP], 1u);
;             const unsigned tg = og / nx;
;             if (og + 1u == (tg + 1u) * nx) xb_add(&bar[XB_TOPGEN], 1u);
;             else XB_SPIN(xb_ld(&bar[XB_TOPGEN]) == tg, bar);
;             __builtin_amdgcn_fence(__ATOMIC_ACQUIRE, "agent");
;             xb_add(&bar[XB_XGEN(b.x)], 1u);
.LBB0_255:
	s_andn2_saveexec_b64 s[6:7], s[6:7]
	s_cbranch_execz .LBB0_271
	s_waitcnt vmcnt(0)
	v_mov_b32_e32 v1, 0x3000
	v_mov_b32_e32 v2, 1
	global_atomic_add v1, v1, v2, s[42:43] offset:1024 sc0
	s_waitcnt lgkmcnt(0)
	v_cvt_f32_u32_e32 v2, v0
	v_sub_u32_e32 v3, 0, v0
	s_add_u32 s6, s42, 0x3500
	s_addc_u32 s7, s43, 0
	v_rcp_iflag_f32_e32 v2, v2
	s_mov_b64 s[10:11], -1
	v_mul_f32_e32 v2, 0x4f7ffffe, v2
	v_cvt_u32_f32_e32 v2, v2
	v_mul_lo_u32 v3, v3, v2
	v_mul_hi_u32 v3, v2, v3
	v_add_u32_e32 v2, v2, v3
	s_waitcnt vmcnt(0)
	buffer_inv sc1
	v_mul_hi_u32 v2, v1, v2
	v_mul_lo_u32 v4, v2, v0
	v_add_u32_e32 v3, 1, v1
	v_sub_u32_e32 v1, v1, v4
	v_add_u32_e32 v5, 1, v2
	v_cmp_ge_u32_e32 vcc, v1, v0
	v_sub_u32_e32 v4, v1, v0
	s_nop 0
	v_cndmask_b32_e32 v2, v2, v5, vcc
	v_cndmask_b32_e32 v1, v1, v4, vcc
	v_add_u32_e32 v4, 1, v2
	v_cmp_ge_u32_e32 vcc, v1, v0
	s_nop 1
	v_cndmask_b32_e32 v2, v2, v4, vcc
	v_mul_lo_u32 v1, v0, v2
	v_add_u32_e32 v0, v1, v0
	v_cmp_ne_u32_e32 vcc, v3, v0
	v_mov_b64_e32 v[0:1], s[6:7]
	s_and_saveexec_b64 s[8:9], vcc
	s_cbranch_execz .LBB0_268
	v_mov_b32_e32 v0, 0
	global_load_dword v1, v0, s[6:7] sc1
	s_mov_b64 s[14:15], 0
	s_waitcnt vmcnt(0)
	v_cmp_eq_u32_e32 vcc, v1, v2
	s_and_saveexec_b64 s[12:13], vcc
	s_cbranch_execz .LBB0_267
	s_add_u32 s10, s42, 0x200
	s_addc_u32 s11, s43, 0
	s_mov_b32 s24, 1
	s_branch .LBB0_260

; __device__ __forceinline__ unsigned xb_ld(unsigned* p)              { return __hip_atomic_load(p, __ATOMIC_RELAXED, __HIP_MEMORY_SCOPE_AGENT); }
; __device__ __forceinline__ unsigned xb_add(unsigned* p, unsigned v) { return __hip_atomic_fetch_add(p, v, __ATOMIC_RELAXED, __HIP_MEMORY_SCOPE_AGENT); }
; #define XB_SPIN(cond, bar) do { unsigned _sp = 0; while (cond) { __builtin_amdgcn_s_sleep(1); \
;     if ((++_sp & 255u) == 0u) { if (xb_ld(&(bar)[XB_TMO])) break; if (_sp > XB_SPIN_CAP) { atomicAdd(&(bar)[XB_TMO], 1u); break; } } } } while (0)
; template <bool FLUSH> __device__ __forceinline__ void xcd_barrier(const XcdBarrier& b) {
;     ...
;         const unsigned old = xb_add(&bar[XB_XSUB(b.x)], 1u);
;         const unsigned gen = old / nloc;
;         if (old + 1u == (gen + 1u) * nloc) {
;             if (FLUSH) __builtin_amdgcn_fence(__ATOMIC_RELEASE, "agent");
;             asm volatile("s_waitcnt vmcnt(0)" ::: "memory");
;             const unsigned og = xb_add(&bar[XB_TOP], 1u);
;             const unsigned tg = og / nx;
;             if (og + 1u == (tg + 1u) * nx) xb_add(&bar[XB_TOPGEN], 1u);
;             else XB_SPIN(xb_ld(&bar[XB_TOPGEN]) == tg, bar);
;             __builtin_amdgcn_fence(__ATOMIC_ACQUIRE, "agent");
;             xb_add(&bar[XB_XGEN(b.x)], 1u);
.LBB0_2212:
	s_andn2_saveexec_b64 s[4:5], s[4:5]
	s_cbranch_execz .LBB0_2228
	buffer_wbl2 sc1
	s_waitcnt lgkmcnt(0)
	s_waitcnt vmcnt(0)
	v_mov_b32_e32 v1, 0x3000
	v_mov_b32_e32 v2, 1
	global_atomic_add v1, v1, v2, s[42:43] offset:1024 sc0
	v_cvt_f32_u32_e32 v2, v0
	v_sub_u32_e32 v3, 0, v0
	s_add_u32 s4, s42, 0x3500
	s_addc_u32 s5, s43, 0
	v_rcp_iflag_f32_e32 v2, v2
	s_mov_b64 s[8:9], -1
	v_mul_f32_e32 v2, 0x4f7ffffe, v2
	v_cvt_u32_f32_e32 v2, v2
	v_mul_lo_u32 v3, v3, v2
	v_mul_hi_u32 v3, v2, v3
	v_add_u32_e32 v2, v2, v3
	s_waitcnt vmcnt(0)
	buffer_inv sc1
	v_mul_hi_u32 v2, v1, v2
	v_mul_lo_u32 v4, v2, v0
	v_add_u32_e32 v3, 1, v1
	v_sub_u32_e32 v1, v1, v4
	v_add_u32_e32 v5, 1, v2
	v_cmp_ge_u32_e32 vcc, v1, v0
	v_sub_u32_e32 v4, v1, v0
	s_nop 0
	v_cndmask_b32_e32 v2, v2, v5, vcc
	v_cndmask_b32_e32 v1, v1, v4, vcc
	v_add_u32_e32 v4, 1, v2
	v_cmp_ge_u32_e32 vcc, v1, v0
	s_nop 1
	v_cndmask_b32_e32 v2, v2, v4, vcc
	v_mul_lo_u32 v1, v0, v2
	v_add_u32_e32 v0, v1, v0
	v_cmp_ne_u32_e32 vcc, v3, v0
	v_mov_b64_e32 v[0:1], s[4:5]
	s_and_saveexec_b64 s[6:7], vcc
	s_cbranch_execz .LBB0_2225
	v_mov_b32_e32 v0, 0
	global_load_dword v1, v0, s[4:5] sc1
	s_mov_b64 s[12:13], 0
	s_waitcnt vmcnt(0)
	v_cmp_eq_u32_e32 vcc, v1, v2
	s_and_saveexec_b64 s[10:11], vcc
	s_cbranch_execz .LBB0_2224
	s_add_u32 s8, s42, 0x200
	s_addc_u32 s9, s43, 0
	s_mov_b32 s22, 1
	s_branch .LBB0_2217

; __device__ __forceinline__ unsigned xb_ld(unsigned* p)              { return __hip_atomic_load(p, __ATOMIC_RELAXED, __HIP_MEMORY_SCOPE_AGENT); }
; __device__ __forceinline__ unsigned xb_add(unsigned* p, unsigned v) { return __hip_atomic_fetch_add(p, v, __ATOMIC_RELAXED, __HIP_MEMORY_SCOPE_AGENT); }
; #define XB_SPIN(cond, bar) do { unsigned _sp = 0; while (cond) { __builtin_amdgcn_s_sleep(1); \
;     if ((++_sp & 255u) == 0u) { if (xb_ld(&(bar)[XB_TMO])) break; if (_sp > XB_SPIN_CAP) { atomicAdd(&(bar)[XB_TMO], 1u); break; } } } } while (0)
; template <bool FLUSH> __device__ __forceinline__ void xcd_barrier(const XcdBarrier& b) {
;     ...
;             if (og + 1u == (tg + 1u) * nx) xb_add(&bar[XB_TOPGEN], 1u);
;             else XB_SPIN(xb_ld(&bar[XB_TOPGEN]) == tg, bar);
;             __builtin_amdgcn_fence(__ATOMIC_ACQUIRE, "agent");
;             xb_add(&bar[XB_XGEN(b.x)], 1u);
;             asm volatile("s_waitcnt vmcnt(0)" ::: "memory");
.LBB0_2227:
	s_or_b64 exec, exec, s[4:5]
	v_mov_b32_e32 v0, 0x2000
	v_mov_b32_e32 v1, 1
	global_atomic_add v0, v1, s[2:3] offset:1024
	s_waitcnt vmcnt(0)
